# StaticOrder::next collapsed to a shift for the multi-round GEMMs (pn = L>>6, pm constant per CU)
# speedup vs baseline: 1.0045x; 1.0045x over previous
.LBB0_90:
	s_add_i32 s63, s63, 1
	v_readlane_b32 s40, v252, 16
	v_readlane_b32 s42, v252, 4
	s_mul_i32 s40, s63, s40
	s_mul_hi_u32 s41, s63, s42
	s_add_i32 s41, s41, s40
	s_mul_i32 s40, s63, s42
	v_readlane_b32 s42, v252, 5
	s_add_u32 s42, s40, s42
	v_readlane_b32 s40, v252, 15
	s_addc_u32 s43, s41, s40
	v_mov_b64_e32 v[4:5], 0x240
	v_cmp_lt_i64_e64 s[40:41], s[42:43], v[4:5]
	v_mov_b64_e32 v[4:5], 0x23f
	v_cmp_gt_i64_e32 vcc, s[42:43], v[4:5]
	s_cbranch_vccnz .LBB0_92
	s_lshr_b32 s46, s42, 6
	s_mov_b32 s52, s44

.LBB0_860:
	s_add_i32 s57, s57, 1
	v_readlane_b32 s29, v252, 16
	v_readlane_b32 s42, v252, 4
	s_mul_i32 s29, s57, s29
	s_mul_hi_u32 s31, s57, s42
	s_add_i32 s31, s31, s29
	s_mul_i32 s29, s57, s42
	v_readlane_b32 s42, v252, 5
	s_add_u32 s44, s29, s42
	v_readlane_b32 s29, v252, 15
	s_addc_u32 s45, s31, s29
	v_cmp_gt_i64_e32 vcc, s[44:45], v[174:175]
	v_cmp_lt_i64_e64 s[42:43], s[44:45], v[172:173]
	s_cbranch_vccnz .LBB0_862
	s_lshr_b32 s28, s44, 6
	s_mov_b32 s30, s59
